# v23 + one static s_setprio 1 for waves 4-7 on entry to the attention phases P2/P3 (reset before P4)
# speedup vs baseline: 1.0058x; 1.0023x over previous
; #define LAS __attribute__((address_space(3)))
; __device__ __forceinline__ unsigned xb_xcc_id() { return (unsigned)__builtin_amdgcn_s_getreg((3 << 11) | 20) & 0xFu; }
; DI int next_unit(unsigned* ctr, char* sm) {
;     volatile LAS int* slot = (volatile LAS int*)(sm + L_MISC);
;     __syncthreads();
;     if (threadIdx.x == 0) *slot = (int)atomicAdd(ctr, 1u);
;     __syncthreads();
;     return *slot;
; }
; __global__ void __launch_bounds__(512, 2) mega_fwd(Params p) {
;     ...
;         xcd_barrier(XcdBarrier{ctl + 1024, xb_xcc_id(), (volatile LAS unsigned*)(sm + L_XB)});
;         for (int u = next_unit(ctl + 2 * l, sm); u < 2816;) {
.LBB0_281:
	s_or_b64 exec, exec, s[0:1]
	v_readfirstlane_b32 s100, v172
	s_lshr_b32 s100, s100, 6
	s_cmp_lt_u32 s100, 4
	s_cbranch_scc1 .Lprio_p2
	s_setprio 1
.Lprio_p2:
	v_readlane_b32 s0, v244, 55
	v_readlane_b32 s1, v244, 56
	s_xor_b64 s[0:1], s[0:1], -1
	v_writelane_b32 v244, s0, 59
	v_readlane_b32 s4, v245, 0
	v_readlane_b32 s6, v245, 2
	v_writelane_b32 v244, s1, 60
	s_mov_b32 s1, s80
	v_readlane_b32 s0, v244, 54
	s_lshl_b32 s0, s0, 1
	s_lshl_b64 s[2:3], s[0:1], 2
	v_readlane_b32 s7, v245, 3
	s_add_u32 s2, s6, s2
	s_addc_u32 s3, s7, s3
	v_writelane_b32 v244, s2, 61
	s_waitcnt lgkmcnt(0)
	s_barrier
	v_readlane_b32 s5, v245, 1
	v_writelane_b32 v244, s3, 62
	s_barrier
	s_and_saveexec_b64 s[2:3], s[72:73]
	s_cbranch_execz .LBB0_285
	s_mov_b64 s[6:7], exec
	v_mbcnt_lo_u32_b32 v0, s6, 0
	v_mbcnt_hi_u32_b32 v0, s7, v0
	v_cmp_eq_u32_e32 vcc, 0, v0
	s_and_saveexec_b64 s[4:5], vcc
	s_cbranch_execz .LBB0_284
	s_bcnt1_i32_b64 s1, s[6:7]
	v_readlane_b32 s6, v244, 61
	v_mov_b32_e32 v2, s1
	v_readlane_b32 s7, v244, 62
	s_nop 4
	global_atomic_add v2, v1, v2, s[6:7] sc0

; #define LAS __attribute__((address_space(3)))
; __device__ __forceinline__ unsigned xb_xcc_id() { return (unsigned)__builtin_amdgcn_s_getreg((3 << 11) | 20) & 0xFu; }
; DI int next_unit(unsigned* ctr, char* sm) {
;     volatile LAS int* slot = (volatile LAS int*)(sm + L_MISC);
;     __syncthreads();
;     if (threadIdx.x == 0) *slot = (int)atomicAdd(ctr, 1u);
;     __syncthreads();
;     return *slot;
; }
; __global__ void __launch_bounds__(512, 2) mega_fwd(Params p) {
;     ...
;         xcd_barrier(XcdBarrier{ctl + 1024, xb_xcc_id(), (volatile LAS unsigned*)(sm + L_XB)});
;         for (int u = next_unit(ctl + 2 * l + 1, sm); u < 1024;) {
.Lprio_p3:
	s_waitcnt lgkmcnt(0)
	s_barrier
	s_barrier
	s_and_saveexec_b64 s[0:1], s[72:73]
	s_cbranch_execz .LBB0_550
	s_mov_b64 s[4:5], exec
	v_mbcnt_lo_u32_b32 v0, s4, 0
	v_mbcnt_hi_u32_b32 v0, s5, v0
	v_cmp_eq_u32_e32 vcc, 0, v0
	s_and_saveexec_b64 s[2:3], vcc
	s_cbranch_execz .LBB0_470
	s_bcnt1_i32_b64 s4, s[4:5]
	v_mov_b32_e32 v2, s4
	v_readlane_b32 s4, v244, 61
	v_readlane_b32 s5, v244, 62
	s_nop 4
	global_atomic_add v2, v1, v2, s[4:5] offset:4 sc0

; #define LAS __attribute__((address_space(3)))
; __device__ __forceinline__ unsigned xb_xcc_id() { return (unsigned)__builtin_amdgcn_s_getreg((3 << 11) | 20) & 0xFu; }
; __device__ __forceinline__ void xcd_barrier(const XcdBarrier& b) {
;     asm volatile("s_waitcnt vmcnt(0)" ::: "memory");
;     __syncthreads();
;     if (threadIdx.x == 0) {
;         unsigned* bar = b.bar;
;         __builtin_amdgcn_s_waitcnt(0);
;         unsigned nloc = b.st[0], nx = b.st[1];
;         if (nloc == 0u) { xcd_barrier_complete(bar, b.x, nloc, nx); b.st[0] = nloc; b.st[1] = nx; }
; __global__ void __launch_bounds__(512, 2) mega_fwd(Params p) {
;     ...
;             { volatile LAS int* slot = (volatile LAS int*)(sm + L_MISC); __syncthreads(); if (threadIdx.x == 0) *slot = nxt_; __syncthreads(); u = *slot; }
;         }
;         xcd_barrier(XcdBarrier{ctl + 1024, xb_xcc_id(), (volatile LAS unsigned*)(sm + L_XB)});
.LBB0_550:
	s_or_b64 exec, exec, s[0:1]
	v_mov_b32_e32 v0, s99
	s_waitcnt lgkmcnt(0)
	s_barrier
	ds_read_b32 v0, v0
	s_movk_i32 s0, 0x3ff
	s_waitcnt lgkmcnt(0)
	v_cmp_lt_i32_e32 vcc, s0, v0
	v_readfirstlane_b32 s6, v0
	s_cbranch_vccz .LBB0_471
	s_setprio 0
	s_getreg_b32 s2, hwreg(HW_REG_XCC_ID, 0, 4)
	s_waitcnt vmcnt(0)
	s_barrier
	s_and_saveexec_b64 s[0:1], s[72:73]
	s_cbranch_execz .LBB0_603
	v_readlane_b32 s3, v244, 48
	s_waitcnt vmcnt(0) expcnt(0) lgkmcnt(0)
	s_and_b32 s8, s2, 15
	v_mov_b32_e32 v0, s3
	ds_read_b32 v3, v0
	v_readlane_b32 s3, v244, 49
	s_waitcnt lgkmcnt(0)
	v_cmp_ne_u32_e32 vcc, 0, v3
	v_mov_b32_e32 v0, s3
	ds_read_b32 v2, v0
	s_cbranch_vccnz .LBB0_567
	s_mov_b32 s9, 1
	s_branch .LBB0_555

; __global__ void __launch_bounds__(512, 2) mega_fwd(Params p) {
;     extern __shared__ __attribute__((aligned(16))) unsigned char smem[];
;     cg::grid_group grid = cg::this_grid();
;     char* sm = (char*)smem;
;     int tid_ = threadIdx.x; asm volatile("" : "+v"(tid_)); const int tid = tid_, lane = tid & 63, wid = __builtin_amdgcn_readfirstlane(tid >> 6);
	.amdhsa_kernel _Z8mega_fwd6Params
		.amdhsa_group_segment_fixed_size 0
		.amdhsa_private_segment_fixed_size 0
		.amdhsa_kernarg_size 368
		.amdhsa_user_sgpr_count 2
		.amdhsa_user_sgpr_dispatch_ptr 0
		.amdhsa_user_sgpr_queue_ptr 0
		.amdhsa_user_sgpr_kernarg_segment_ptr 1
		.amdhsa_user_sgpr_dispatch_id 0
		.amdhsa_user_sgpr_kernarg_preload_length 0
		.amdhsa_user_sgpr_kernarg_preload_offset 0
		.amdhsa_user_sgpr_private_segment_size 0
		.amdhsa_uses_dynamic_stack 0
		.amdhsa_enable_private_segment 0
		.amdhsa_system_sgpr_workgroup_id_x 1
		.amdhsa_system_sgpr_workgroup_id_y 0
		.amdhsa_system_sgpr_workgroup_id_z 0
		.amdhsa_system_sgpr_workgroup_info 0
		.amdhsa_system_vgpr_workitem_id 2
		.amdhsa_next_free_vgpr 256
		.amdhsa_next_free_sgpr 101
		.amdhsa_accum_offset 256
		.amdhsa_reserve_vcc 1
		.amdhsa_float_round_mode_32 0
		.amdhsa_float_round_mode_16_64 0
		.amdhsa_float_denorm_mode_32 3
		.amdhsa_float_denorm_mode_16_64 3
		.amdhsa_dx10_clamp 1
		.amdhsa_ieee_mode 1
		.amdhsa_fp16_overflow 0
		.amdhsa_tg_split 0
		.amdhsa_exception_fp_ieee_invalid_op 0
		.amdhsa_exception_fp_denorm_src 0
		.amdhsa_exception_fp_ieee_div_zero 0
		.amdhsa_exception_fp_ieee_overflow 0
		.amdhsa_exception_fp_ieee_underflow 0
		.amdhsa_exception_fp_ieee_inexact 0
		.amdhsa_exception_int_div_zero 0
	.end_amdhsa_kernel
